# od_in (GELU) epilogue: the 8 per-row-group ssq loads batched into one round trip
# baseline (speedup 1.0000x reference)
.LBB0_928:
	v_lshl_add_u32 v134, s13, 8, v145
	v_ashrrev_i32_e32 v135, 31, v134
	v_lshl_add_u64 v[136:137], v[134:135], 2, s[36:37]
	global_load_dword v160, v[136:137], off
	global_load_dword v161, v[136:137], off offset:64
	global_load_dword v162, v[136:137], off offset:128
	global_load_dword v163, v[136:137], off offset:192
	global_load_dword v164, v[136:137], off offset:512
	global_load_dword v165, v[136:137], off offset:576
	global_load_dword v166, v[136:137], off offset:640
	global_load_dword v167, v[136:137], off offset:704
	s_mov_b32 s2, 0x800000
	s_cmp_lt_i32 s12, 4
	s_movk_i32 s0, 0xf800
	s_cselect_b64 s[10:11], -1, 0
	s_cmp_gt_i32 s12, 3
	s_mov_b32 s1, -1
	s_waitcnt vmcnt(0)
	v_fmamk_f32 v138, v160, 0x3a800000, v227
	v_mul_f32_e32 v139, 0x4b800000, v138
	v_cmp_gt_f32_e32 vcc, s2, v138
	s_nop 1
	v_cndmask_b32_e32 v138, v138, v139, vcc
	v_rsq_f32_e32 v138, v138
	s_nop 0
	v_mul_f32_e32 v139, 0x45800000, v138
	v_cndmask_b32_e32 v138, v138, v139, vcc
	v_pk_mul_f32 v[126:127], v[126:127], v[138:139] op_sel_hi:[1,0]
	v_pk_mul_f32 v[124:125], v[124:125], v[138:139] op_sel_hi:[1,0]
	v_pk_mul_f32 v[140:141], v[122:123], v[138:139] op_sel_hi:[1,0]
	v_pk_mul_f32 v[142:143], v[120:121], v[138:139] op_sel_hi:[1,0]
	s_cbranch_scc1 .LBB0_930
	v_mul_f32_e32 v121, 0x3d372713, v142
	v_mul_f32_e32 v121, v142, v121
	v_fma_f32 v121, v142, v121, v142
	v_mul_f32_e32 v121, 0x3f4c422a, v121
	v_add_f32_e32 v121, v121, v121
	v_mul_f32_e32 v121, 0xbfb8aa3b, v121
	v_exp_f32_e32 v121, v121
	v_mov_b32_e32 v123, v125
	v_mov_b32_e32 v139, v143
	v_mul_f32_e32 v120, 0x3d372713, v124
	v_add_f32_e32 v121, 1.0, v121
	v_rcp_f32_e32 v122, v121
	v_mul_f32_e32 v121, 0x3d372713, v125
	v_mul_f32_e32 v121, v125, v121
	v_fmac_f32_e32 v123, v123, v121
	v_mul_f32_e32 v121, 0x3f4c422a, v123
	v_mul_f32_e32 v123, 0x3d372713, v143
	v_mul_f32_e32 v123, v143, v123
	v_fmac_f32_e32 v139, v139, v123
	v_mul_f32_e32 v123, 0x3f4c422a, v139
	v_mul_f32_e32 v139, 0x3d372713, v126
	v_mul_f32_e32 v139, v126, v139
	v_fma_f32 v139, v126, v139, v126
	v_mul_f32_e32 v139, 0x3f4c422a, v139
	v_add_f32_e32 v139, v139, v139
	v_mul_f32_e32 v139, 0xbfb8aa3b, v139
	v_exp_f32_e32 v139, v139
	v_mul_f32_e32 v120, v124, v120
	v_fma_f32 v120, v124, v120, v124
	v_mul_f32_e32 v120, 0x3f4c422a, v120
	v_add_f32_e32 v139, 1.0, v139
	v_add_f32_e32 v120, v120, v120
	v_add_f32_e32 v121, v121, v121
	v_rcp_f32_e32 v150, v139
	v_mul_f32_e32 v139, 0x3d372713, v140
	v_mul_f32_e32 v120, 0xbfb8aa3b, v120
	v_mul_f32_e32 v121, 0xbfb8aa3b, v121
	v_mul_f32_e32 v139, v140, v139
	v_exp_f32_e32 v120, v120
	v_exp_f32_e32 v121, v121
	v_fma_f32 v139, v140, v139, v140
	v_mul_f32_e32 v139, 0x3f4c422a, v139
	v_add_f32_e32 v139, v139, v139
	v_mul_f32_e32 v139, 0xbfb8aa3b, v139
	v_add_f32_e32 v120, 1.0, v120
	v_add_f32_e32 v121, 1.0, v121
	v_exp_f32_e32 v139, v139
	v_rcp_f32_e32 v120, v120
	v_rcp_f32_e32 v121, v121
	v_add_f32_e32 v123, v123, v123
	v_add_f32_e32 v139, 1.0, v139
	v_rcp_f32_e32 v152, v139
	v_mul_f32_e32 v139, 0x3d372713, v127
	v_pk_mul_f32 v[124:125], v[124:125], v[120:121]
	v_mul_f32_e32 v120, 0x3d372713, v141
	v_mul_f32_e32 v139, v127, v139
	v_mul_f32_e32 v120, v141, v120
	v_fma_f32 v139, v127, v139, v127
	v_fma_f32 v120, v141, v120, v141
	v_mul_f32_e32 v139, 0x3f4c422a, v139
	v_mul_f32_e32 v120, 0x3f4c422a, v120
	v_add_f32_e32 v139, v139, v139
	v_add_f32_e32 v120, v120, v120
	v_mul_f32_e32 v123, 0xbfb8aa3b, v123
	v_mul_f32_e32 v139, 0xbfb8aa3b, v139
	v_mul_f32_e32 v120, 0xbfb8aa3b, v120
	v_exp_f32_e32 v123, v123
	v_exp_f32_e32 v139, v139
	v_exp_f32_e32 v120, v120
	v_add_f32_e32 v123, 1.0, v123
	v_add_f32_e32 v139, 1.0, v139
	v_add_f32_e32 v120, 1.0, v120
	v_rcp_f32_e32 v123, v123
	v_rcp_f32_e32 v151, v139
	v_rcp_f32_e32 v153, v120
	v_pk_mul_f32 v[142:143], v[142:143], v[122:123]
	v_pk_mul_f32 v[126:127], v[126:127], v[150:151]
	v_pk_mul_f32 v[140:141], v[140:141], v[152:153]

.LBB0_932:
	v_cvt_pk_bf16_f32 v116, v116, v117
	v_cvt_pk_bf16_f32 v117, v118, v119
	v_cvt_pk_bf16_f32 v119, v114, v115
	v_or_b32_e32 v114, 16, v134
	v_cvt_pk_bf16_f32 v118, v112, v113
	v_ashrrev_i32_e32 v115, 31, v114
	global_store_dwordx4 v[122:123], v[116:119], off offset:256
	v_lshl_add_u64 v[112:113], v[114:115], 2, s[36:37]
	s_and_b64 vcc, exec, s[12:13]
	v_fmamk_f32 v112, v161, 0x3a800000, v227
	v_mul_f32_e32 v113, 0x4b800000, v112
	v_cmp_gt_f32_e64 s[16:17], s2, v112
	s_nop 1
	v_cndmask_b32_e64 v112, v112, v113, s[16:17]
	v_rsq_f32_e32 v112, v112
	s_nop 0
	v_mul_f32_e32 v113, 0x45800000, v112
	v_cndmask_b32_e64 v112, v112, v113, s[16:17]
	v_pk_mul_f32 v[110:111], v[110:111], v[112:113] op_sel_hi:[1,0]
	v_pk_mul_f32 v[116:117], v[108:109], v[112:113] op_sel_hi:[1,0]
	v_pk_mul_f32 v[106:107], v[106:107], v[112:113] op_sel_hi:[1,0]
	v_pk_mul_f32 v[108:109], v[104:105], v[112:113] op_sel_hi:[1,0]
	s_cbranch_vccnz .LBB0_934
	v_mul_f32_e32 v105, 0x3d372713, v108
	v_mul_f32_e32 v105, v108, v105
	v_fma_f32 v105, v108, v105, v108
	v_mul_f32_e32 v105, 0x3f4c422a, v105
	v_add_f32_e32 v105, v105, v105
	v_mul_f32_e32 v105, 0xbfb8aa3b, v105
	v_exp_f32_e32 v105, v105
	v_mov_b32_e32 v113, v117
	v_mov_b32_e32 v119, v109
	v_mul_f32_e32 v104, 0x3d372713, v116
	v_add_f32_e32 v105, 1.0, v105
	v_rcp_f32_e32 v118, v105
	v_mul_f32_e32 v105, 0x3d372713, v117
	v_mul_f32_e32 v105, v117, v105
	v_fmac_f32_e32 v113, v113, v105
	v_mul_f32_e32 v105, 0x3f4c422a, v113
	v_mul_f32_e32 v113, 0x3d372713, v109
	v_mul_f32_e32 v113, v109, v113
	v_fmac_f32_e32 v119, v119, v113
	v_mul_f32_e32 v113, 0x3f4c422a, v119
	v_add_f32_e32 v113, v113, v113
	v_mul_f32_e32 v113, 0xbfb8aa3b, v113
	v_exp_f32_e32 v113, v113
	v_mul_f32_e32 v104, v116, v104
	v_fma_f32 v104, v116, v104, v116
	v_mul_f32_e32 v104, 0x3f4c422a, v104
	v_add_f32_e32 v113, 1.0, v113
	v_rcp_f32_e32 v119, v113
	v_mul_f32_e32 v113, 0x3d372713, v110
	v_mul_f32_e32 v113, v110, v113
	v_fma_f32 v113, v110, v113, v110
	v_mul_f32_e32 v113, 0x3f4c422a, v113
	v_add_f32_e32 v113, v113, v113
	v_mul_f32_e32 v113, 0xbfb8aa3b, v113
	v_exp_f32_e32 v113, v113
	v_add_f32_e32 v104, v104, v104
	v_add_f32_e32 v105, v105, v105
	v_mul_f32_e32 v104, 0xbfb8aa3b, v104
	v_add_f32_e32 v113, 1.0, v113
	v_rcp_f32_e32 v122, v113
	v_mul_f32_e32 v113, 0x3d372713, v106
	v_mul_f32_e32 v105, 0xbfb8aa3b, v105
	v_mul_f32_e32 v113, v106, v113
	v_exp_f32_e32 v104, v104
	v_exp_f32_e32 v105, v105
	v_fma_f32 v113, v106, v113, v106
	v_mul_f32_e32 v113, 0x3f4c422a, v113
	v_add_f32_e32 v113, v113, v113
	v_mul_f32_e32 v113, 0xbfb8aa3b, v113
	v_add_f32_e32 v104, 1.0, v104
	v_add_f32_e32 v105, 1.0, v105
	v_exp_f32_e32 v113, v113
	v_rcp_f32_e32 v104, v104
	v_rcp_f32_e32 v105, v105
	v_pk_mul_f32 v[108:109], v[108:109], v[118:119]
	v_add_f32_e32 v113, 1.0, v113
	v_rcp_f32_e32 v124, v113
	v_mul_f32_e32 v113, 0x3d372713, v111
	v_pk_mul_f32 v[116:117], v[116:117], v[104:105]
	v_mul_f32_e32 v104, 0x3d372713, v107
	v_mul_f32_e32 v113, v111, v113
	v_mul_f32_e32 v104, v107, v104
	v_fma_f32 v113, v111, v113, v111
	v_fma_f32 v104, v107, v104, v107
	v_mul_f32_e32 v113, 0x3f4c422a, v113
	v_mul_f32_e32 v104, 0x3f4c422a, v104
	v_add_f32_e32 v113, v113, v113
	v_add_f32_e32 v104, v104, v104
	v_mul_f32_e32 v113, 0xbfb8aa3b, v113
	v_mul_f32_e32 v104, 0xbfb8aa3b, v104
	v_exp_f32_e32 v113, v113
	v_exp_f32_e32 v104, v104
	v_add_f32_e32 v113, 1.0, v113
	v_add_f32_e32 v104, 1.0, v104
	v_rcp_f32_e32 v123, v113
	v_rcp_f32_e32 v125, v104
	v_pk_mul_f32 v[110:111], v[110:111], v[122:123]
	v_pk_mul_f32 v[106:107], v[106:107], v[124:125]

.LBB0_936:
	v_cvt_pk_bf16_f32 v100, v100, v101
	v_cvt_pk_bf16_f32 v101, v102, v103
	v_cvt_pk_bf16_f32 v103, v98, v99
	v_or_b32_e32 v98, 32, v134
	v_cvt_pk_bf16_f32 v102, v96, v97
	v_ashrrev_i32_e32 v99, 31, v98
	global_store_dwordx4 v[104:105], v[100:103], off offset:256
	v_lshl_add_u64 v[96:97], v[98:99], 2, s[36:37]
	s_and_b64 vcc, exec, s[12:13]
	v_fmamk_f32 v96, v162, 0x3a800000, v227
	v_mul_f32_e32 v97, 0x4b800000, v96
	v_cmp_gt_f32_e64 s[16:17], s2, v96
	s_nop 1
	v_cndmask_b32_e64 v96, v96, v97, s[16:17]
	v_rsq_f32_e32 v96, v96
	s_nop 0
	v_mul_f32_e32 v97, 0x45800000, v96
	v_cndmask_b32_e64 v96, v96, v97, s[16:17]
	v_pk_mul_f32 v[94:95], v[94:95], v[96:97] op_sel_hi:[1,0]
	v_pk_mul_f32 v[100:101], v[92:93], v[96:97] op_sel_hi:[1,0]
	v_pk_mul_f32 v[90:91], v[90:91], v[96:97] op_sel_hi:[1,0]
	v_pk_mul_f32 v[92:93], v[88:89], v[96:97] op_sel_hi:[1,0]
	s_cbranch_vccnz .LBB0_938
	v_mul_f32_e32 v89, 0x3d372713, v92
	v_mul_f32_e32 v89, v92, v89
	v_fma_f32 v89, v92, v89, v92
	v_mul_f32_e32 v89, 0x3f4c422a, v89
	v_add_f32_e32 v89, v89, v89
	v_mul_f32_e32 v89, 0xbfb8aa3b, v89
	v_exp_f32_e32 v89, v89
	v_mov_b32_e32 v97, v101
	v_mov_b32_e32 v103, v93
	v_mul_f32_e32 v88, 0x3d372713, v100
	v_add_f32_e32 v89, 1.0, v89
	v_rcp_f32_e32 v102, v89
	v_mul_f32_e32 v89, 0x3d372713, v101
	v_mul_f32_e32 v89, v101, v89
	v_fmac_f32_e32 v97, v97, v89
	v_mul_f32_e32 v89, 0x3f4c422a, v97
	v_mul_f32_e32 v97, 0x3d372713, v93
	v_mul_f32_e32 v97, v93, v97
	v_fmac_f32_e32 v103, v103, v97
	v_mul_f32_e32 v97, 0x3f4c422a, v103
	v_add_f32_e32 v97, v97, v97
	v_mul_f32_e32 v97, 0xbfb8aa3b, v97
	v_exp_f32_e32 v97, v97
	v_mul_f32_e32 v88, v100, v88
	v_fma_f32 v88, v100, v88, v100
	v_mul_f32_e32 v88, 0x3f4c422a, v88
	v_add_f32_e32 v97, 1.0, v97
	v_rcp_f32_e32 v103, v97
	v_mul_f32_e32 v97, 0x3d372713, v94
	v_mul_f32_e32 v97, v94, v97
	v_fma_f32 v97, v94, v97, v94
	v_mul_f32_e32 v97, 0x3f4c422a, v97
	v_add_f32_e32 v97, v97, v97
	v_mul_f32_e32 v97, 0xbfb8aa3b, v97
	v_exp_f32_e32 v97, v97
	v_add_f32_e32 v88, v88, v88
	v_add_f32_e32 v89, v89, v89
	v_mul_f32_e32 v88, 0xbfb8aa3b, v88
	v_add_f32_e32 v97, 1.0, v97
	v_rcp_f32_e32 v104, v97
	v_mul_f32_e32 v97, 0x3d372713, v90
	v_mul_f32_e32 v89, 0xbfb8aa3b, v89
	v_mul_f32_e32 v97, v90, v97
	v_exp_f32_e32 v88, v88
	v_exp_f32_e32 v89, v89
	v_fma_f32 v97, v90, v97, v90
	v_mul_f32_e32 v97, 0x3f4c422a, v97
	v_add_f32_e32 v97, v97, v97
	v_mul_f32_e32 v97, 0xbfb8aa3b, v97
	v_add_f32_e32 v88, 1.0, v88
	v_add_f32_e32 v89, 1.0, v89
	v_exp_f32_e32 v97, v97
	v_rcp_f32_e32 v88, v88
	v_rcp_f32_e32 v89, v89
	v_pk_mul_f32 v[92:93], v[92:93], v[102:103]
	v_add_f32_e32 v97, 1.0, v97
	v_rcp_f32_e32 v106, v97
	v_mul_f32_e32 v97, 0x3d372713, v95
	v_pk_mul_f32 v[100:101], v[100:101], v[88:89]
	v_mul_f32_e32 v88, 0x3d372713, v91
	v_mul_f32_e32 v97, v95, v97
	v_mul_f32_e32 v88, v91, v88
	v_fma_f32 v97, v95, v97, v95
	v_fma_f32 v88, v91, v88, v91
	v_mul_f32_e32 v97, 0x3f4c422a, v97
	v_mul_f32_e32 v88, 0x3f4c422a, v88
	v_add_f32_e32 v97, v97, v97
	v_add_f32_e32 v88, v88, v88
	v_mul_f32_e32 v97, 0xbfb8aa3b, v97
	v_mul_f32_e32 v88, 0xbfb8aa3b, v88
	v_exp_f32_e32 v97, v97
	v_exp_f32_e32 v88, v88
	v_add_f32_e32 v97, 1.0, v97
	v_add_f32_e32 v88, 1.0, v88
	v_rcp_f32_e32 v105, v97
	v_rcp_f32_e32 v107, v88
	v_pk_mul_f32 v[94:95], v[94:95], v[104:105]
	v_pk_mul_f32 v[90:91], v[90:91], v[106:107]

.LBB0_940:
	v_cvt_pk_bf16_f32 v84, v84, v85
	v_cvt_pk_bf16_f32 v85, v86, v87
	v_cvt_pk_bf16_f32 v87, v82, v83
	v_or_b32_e32 v82, 48, v134
	v_cvt_pk_bf16_f32 v86, v80, v81
	v_ashrrev_i32_e32 v83, 31, v82
	global_store_dwordx4 v[88:89], v[84:87], off offset:256
	v_lshl_add_u64 v[80:81], v[82:83], 2, s[36:37]
	s_and_b64 vcc, exec, s[12:13]
	v_fmamk_f32 v80, v163, 0x3a800000, v227
	v_mul_f32_e32 v81, 0x4b800000, v80
	v_cmp_gt_f32_e64 s[16:17], s2, v80
	s_nop 1
	v_cndmask_b32_e64 v80, v80, v81, s[16:17]
	v_rsq_f32_e32 v80, v80
	s_nop 0
	v_mul_f32_e32 v81, 0x45800000, v80
	v_cndmask_b32_e64 v80, v80, v81, s[16:17]
	v_pk_mul_f32 v[78:79], v[78:79], v[80:81] op_sel_hi:[1,0]
	v_pk_mul_f32 v[84:85], v[76:77], v[80:81] op_sel_hi:[1,0]
	v_pk_mul_f32 v[74:75], v[74:75], v[80:81] op_sel_hi:[1,0]
	v_pk_mul_f32 v[76:77], v[72:73], v[80:81] op_sel_hi:[1,0]
	s_cbranch_vccnz .LBB0_942
	v_mul_f32_e32 v73, 0x3d372713, v76
	v_mul_f32_e32 v73, v76, v73
	v_fma_f32 v73, v76, v73, v76
	v_mul_f32_e32 v73, 0x3f4c422a, v73
	v_add_f32_e32 v73, v73, v73
	v_mul_f32_e32 v73, 0xbfb8aa3b, v73
	v_exp_f32_e32 v73, v73
	v_mov_b32_e32 v81, v85
	v_mov_b32_e32 v87, v77
	v_mul_f32_e32 v72, 0x3d372713, v84
	v_add_f32_e32 v73, 1.0, v73
	v_rcp_f32_e32 v86, v73
	v_mul_f32_e32 v73, 0x3d372713, v85
	v_mul_f32_e32 v73, v85, v73
	v_fmac_f32_e32 v81, v81, v73
	v_mul_f32_e32 v73, 0x3f4c422a, v81
	v_mul_f32_e32 v81, 0x3d372713, v77
	v_mul_f32_e32 v81, v77, v81
	v_fmac_f32_e32 v87, v87, v81
	v_mul_f32_e32 v81, 0x3f4c422a, v87
	v_add_f32_e32 v81, v81, v81
	v_mul_f32_e32 v81, 0xbfb8aa3b, v81
	v_exp_f32_e32 v81, v81
	v_mul_f32_e32 v72, v84, v72
	v_fma_f32 v72, v84, v72, v84
	v_mul_f32_e32 v72, 0x3f4c422a, v72
	v_add_f32_e32 v81, 1.0, v81
	v_rcp_f32_e32 v87, v81
	v_mul_f32_e32 v81, 0x3d372713, v78
	v_mul_f32_e32 v81, v78, v81
	v_fma_f32 v81, v78, v81, v78
	v_mul_f32_e32 v81, 0x3f4c422a, v81
	v_add_f32_e32 v81, v81, v81
	v_mul_f32_e32 v81, 0xbfb8aa3b, v81
	v_exp_f32_e32 v81, v81
	v_add_f32_e32 v72, v72, v72
	v_add_f32_e32 v73, v73, v73
	v_mul_f32_e32 v72, 0xbfb8aa3b, v72
	v_add_f32_e32 v81, 1.0, v81
	v_rcp_f32_e32 v88, v81
	v_mul_f32_e32 v81, 0x3d372713, v74
	v_mul_f32_e32 v73, 0xbfb8aa3b, v73
	v_mul_f32_e32 v81, v74, v81
	v_exp_f32_e32 v72, v72
	v_exp_f32_e32 v73, v73
	v_fma_f32 v81, v74, v81, v74
	v_mul_f32_e32 v81, 0x3f4c422a, v81
	v_add_f32_e32 v81, v81, v81
	v_mul_f32_e32 v81, 0xbfb8aa3b, v81
	v_add_f32_e32 v72, 1.0, v72
	v_add_f32_e32 v73, 1.0, v73
	v_exp_f32_e32 v81, v81
	v_rcp_f32_e32 v72, v72
	v_rcp_f32_e32 v73, v73
	v_pk_mul_f32 v[76:77], v[76:77], v[86:87]
	v_add_f32_e32 v81, 1.0, v81
	v_rcp_f32_e32 v90, v81
	v_mul_f32_e32 v81, 0x3d372713, v79
	v_pk_mul_f32 v[84:85], v[84:85], v[72:73]
	v_mul_f32_e32 v72, 0x3d372713, v75
	v_mul_f32_e32 v81, v79, v81
	v_mul_f32_e32 v72, v75, v72
	v_fma_f32 v81, v79, v81, v79
	v_fma_f32 v72, v75, v72, v75
	v_mul_f32_e32 v81, 0x3f4c422a, v81
	v_mul_f32_e32 v72, 0x3f4c422a, v72
	v_add_f32_e32 v81, v81, v81
	v_add_f32_e32 v72, v72, v72
	v_mul_f32_e32 v81, 0xbfb8aa3b, v81
	v_mul_f32_e32 v72, 0xbfb8aa3b, v72
	v_exp_f32_e32 v81, v81
	v_exp_f32_e32 v72, v72
	v_add_f32_e32 v81, 1.0, v81
	v_add_f32_e32 v72, 1.0, v72
	v_rcp_f32_e32 v89, v81
	v_rcp_f32_e32 v91, v72
	v_pk_mul_f32 v[78:79], v[78:79], v[88:89]
	v_pk_mul_f32 v[74:75], v[74:75], v[90:91]

.LBB0_944:
	v_cvt_pk_bf16_f32 v68, v68, v69
	v_cvt_pk_bf16_f32 v69, v70, v71
	v_cvt_pk_bf16_f32 v70, v64, v65
	v_cvt_pk_bf16_f32 v71, v66, v67
	global_store_dwordx4 v[72:73], v[68:71], off offset:256
	s_and_b64 vcc, exec, s[12:13]
	v_fmamk_f32 v64, v164, 0x3a800000, v227
	v_mul_f32_e32 v65, 0x4b800000, v64
	v_cmp_gt_f32_e64 s[16:17], s2, v64
	s_nop 1
	v_cndmask_b32_e64 v64, v64, v65, s[16:17]
	v_rsq_f32_e32 v64, v64
	s_nop 0
	v_mul_f32_e32 v65, 0x45800000, v64
	v_cndmask_b32_e64 v64, v64, v65, s[16:17]
	v_pk_mul_f32 v[62:63], v[62:63], v[64:65] op_sel_hi:[1,0]
	v_pk_mul_f32 v[66:67], v[60:61], v[64:65] op_sel_hi:[1,0]
	v_pk_mul_f32 v[58:59], v[58:59], v[64:65] op_sel_hi:[1,0]
	v_pk_mul_f32 v[60:61], v[56:57], v[64:65] op_sel_hi:[1,0]
	s_cbranch_vccnz .LBB0_946
	v_mul_f32_e32 v57, 0x3d372713, v60
	v_mul_f32_e32 v57, v60, v57
	v_fma_f32 v57, v60, v57, v60
	v_mul_f32_e32 v57, 0x3f4c422a, v57
	v_add_f32_e32 v57, v57, v57
	v_mul_f32_e32 v57, 0xbfb8aa3b, v57
	v_exp_f32_e32 v57, v57
	v_mov_b32_e32 v65, v67
	v_mov_b32_e32 v69, v61
	v_mul_f32_e32 v56, 0x3d372713, v66
	v_add_f32_e32 v57, 1.0, v57
	v_rcp_f32_e32 v68, v57
	v_mul_f32_e32 v57, 0x3d372713, v67
	v_mul_f32_e32 v57, v67, v57
	v_fmac_f32_e32 v65, v65, v57
	v_mul_f32_e32 v57, 0x3f4c422a, v65
	v_mul_f32_e32 v65, 0x3d372713, v61
	v_mul_f32_e32 v65, v61, v65
	v_fmac_f32_e32 v69, v69, v65
	v_mul_f32_e32 v65, 0x3f4c422a, v69
	v_add_f32_e32 v65, v65, v65
	v_mul_f32_e32 v65, 0xbfb8aa3b, v65
	v_exp_f32_e32 v65, v65
	v_mul_f32_e32 v56, v66, v56
	v_fma_f32 v56, v66, v56, v66
	v_mul_f32_e32 v56, 0x3f4c422a, v56
	v_add_f32_e32 v65, 1.0, v65
	v_rcp_f32_e32 v69, v65
	v_mul_f32_e32 v65, 0x3d372713, v62
	v_mul_f32_e32 v65, v62, v65
	v_fma_f32 v65, v62, v65, v62
	v_mul_f32_e32 v65, 0x3f4c422a, v65
	v_add_f32_e32 v65, v65, v65
	v_mul_f32_e32 v65, 0xbfb8aa3b, v65
	v_exp_f32_e32 v65, v65
	v_add_f32_e32 v56, v56, v56
	v_add_f32_e32 v57, v57, v57
	v_mul_f32_e32 v56, 0xbfb8aa3b, v56
	v_add_f32_e32 v65, 1.0, v65
	v_rcp_f32_e32 v70, v65
	v_mul_f32_e32 v65, 0x3d372713, v58
	v_mul_f32_e32 v57, 0xbfb8aa3b, v57
	v_mul_f32_e32 v65, v58, v65
	v_exp_f32_e32 v56, v56
	v_exp_f32_e32 v57, v57
	v_fma_f32 v65, v58, v65, v58
	v_mul_f32_e32 v65, 0x3f4c422a, v65
	v_add_f32_e32 v65, v65, v65
	v_mul_f32_e32 v65, 0xbfb8aa3b, v65
	v_add_f32_e32 v56, 1.0, v56
	v_add_f32_e32 v57, 1.0, v57
	v_exp_f32_e32 v65, v65
	v_rcp_f32_e32 v56, v56
	v_rcp_f32_e32 v57, v57
	v_pk_mul_f32 v[60:61], v[60:61], v[68:69]
	v_add_f32_e32 v65, 1.0, v65
	v_rcp_f32_e32 v72, v65
	v_mul_f32_e32 v65, 0x3d372713, v63
	v_pk_mul_f32 v[66:67], v[66:67], v[56:57]
	v_mul_f32_e32 v56, 0x3d372713, v59
	v_mul_f32_e32 v65, v63, v65
	v_mul_f32_e32 v56, v59, v56
	v_fma_f32 v65, v63, v65, v63
	v_fma_f32 v56, v59, v56, v59
	v_mul_f32_e32 v65, 0x3f4c422a, v65
	v_mul_f32_e32 v56, 0x3f4c422a, v56
	v_add_f32_e32 v65, v65, v65
	v_add_f32_e32 v56, v56, v56
	v_mul_f32_e32 v65, 0xbfb8aa3b, v65
	v_mul_f32_e32 v56, 0xbfb8aa3b, v56
	v_exp_f32_e32 v65, v65
	v_exp_f32_e32 v56, v56
	v_add_f32_e32 v65, 1.0, v65
	v_add_f32_e32 v56, 1.0, v56
	v_rcp_f32_e32 v71, v65
	v_rcp_f32_e32 v73, v56
	v_pk_mul_f32 v[62:63], v[62:63], v[70:71]
	v_pk_mul_f32 v[58:59], v[58:59], v[72:73]

.LBB0_948:
	v_cvt_pk_bf16_f32 v52, v52, v53
	v_cvt_pk_bf16_f32 v53, v54, v55
	v_cvt_pk_bf16_f32 v54, v48, v49
	v_cvt_pk_bf16_f32 v55, v50, v51
	global_store_dwordx4 v[56:57], v[52:55], off offset:256
	s_and_b64 vcc, exec, s[12:13]
	v_fmamk_f32 v48, v165, 0x3a800000, v227
	v_mul_f32_e32 v49, 0x4b800000, v48
	v_cmp_gt_f32_e64 s[16:17], s2, v48
	s_nop 1
	v_cndmask_b32_e64 v48, v48, v49, s[16:17]
	v_rsq_f32_e32 v48, v48
	s_nop 0
	v_mul_f32_e32 v49, 0x45800000, v48
	v_cndmask_b32_e64 v48, v48, v49, s[16:17]
	v_pk_mul_f32 v[46:47], v[46:47], v[48:49] op_sel_hi:[1,0]
	v_pk_mul_f32 v[50:51], v[44:45], v[48:49] op_sel_hi:[1,0]
	v_pk_mul_f32 v[42:43], v[42:43], v[48:49] op_sel_hi:[1,0]
	v_pk_mul_f32 v[44:45], v[40:41], v[48:49] op_sel_hi:[1,0]
	s_cbranch_vccnz .LBB0_950
	v_mul_f32_e32 v41, 0x3d372713, v44
	v_mul_f32_e32 v41, v44, v41
	v_fma_f32 v41, v44, v41, v44
	v_mul_f32_e32 v41, 0x3f4c422a, v41
	v_add_f32_e32 v41, v41, v41
	v_mul_f32_e32 v41, 0xbfb8aa3b, v41
	v_exp_f32_e32 v41, v41
	v_mov_b32_e32 v49, v51
	v_mov_b32_e32 v53, v45
	v_mul_f32_e32 v40, 0x3d372713, v50
	v_add_f32_e32 v41, 1.0, v41
	v_rcp_f32_e32 v52, v41
	v_mul_f32_e32 v41, 0x3d372713, v51
	v_mul_f32_e32 v41, v51, v41
	v_fmac_f32_e32 v49, v49, v41
	v_mul_f32_e32 v41, 0x3f4c422a, v49
	v_mul_f32_e32 v49, 0x3d372713, v45
	v_mul_f32_e32 v49, v45, v49
	v_fmac_f32_e32 v53, v53, v49
	v_mul_f32_e32 v49, 0x3f4c422a, v53
	v_add_f32_e32 v49, v49, v49
	v_mul_f32_e32 v49, 0xbfb8aa3b, v49
	v_exp_f32_e32 v49, v49
	v_mul_f32_e32 v40, v50, v40
	v_fma_f32 v40, v50, v40, v50
	v_mul_f32_e32 v40, 0x3f4c422a, v40
	v_add_f32_e32 v49, 1.0, v49
	v_rcp_f32_e32 v53, v49
	v_mul_f32_e32 v49, 0x3d372713, v46
	v_mul_f32_e32 v49, v46, v49
	v_fma_f32 v49, v46, v49, v46
	v_mul_f32_e32 v49, 0x3f4c422a, v49
	v_add_f32_e32 v49, v49, v49
	v_mul_f32_e32 v49, 0xbfb8aa3b, v49
	v_exp_f32_e32 v49, v49
	v_add_f32_e32 v40, v40, v40
	v_add_f32_e32 v41, v41, v41
	v_mul_f32_e32 v40, 0xbfb8aa3b, v40
	v_add_f32_e32 v49, 1.0, v49
	v_rcp_f32_e32 v54, v49
	v_mul_f32_e32 v49, 0x3d372713, v42
	v_mul_f32_e32 v41, 0xbfb8aa3b, v41
	v_mul_f32_e32 v49, v42, v49
	v_exp_f32_e32 v40, v40
	v_exp_f32_e32 v41, v41
	v_fma_f32 v49, v42, v49, v42
	v_mul_f32_e32 v49, 0x3f4c422a, v49
	v_add_f32_e32 v49, v49, v49
	v_mul_f32_e32 v49, 0xbfb8aa3b, v49
	v_add_f32_e32 v40, 1.0, v40
	v_add_f32_e32 v41, 1.0, v41
	v_exp_f32_e32 v49, v49
	v_rcp_f32_e32 v40, v40
	v_rcp_f32_e32 v41, v41
	v_pk_mul_f32 v[44:45], v[44:45], v[52:53]
	v_add_f32_e32 v49, 1.0, v49
	v_rcp_f32_e32 v56, v49
	v_mul_f32_e32 v49, 0x3d372713, v47
	v_pk_mul_f32 v[50:51], v[50:51], v[40:41]
	v_mul_f32_e32 v40, 0x3d372713, v43
	v_mul_f32_e32 v49, v47, v49
	v_mul_f32_e32 v40, v43, v40
	v_fma_f32 v49, v47, v49, v47
	v_fma_f32 v40, v43, v40, v43
	v_mul_f32_e32 v49, 0x3f4c422a, v49
	v_mul_f32_e32 v40, 0x3f4c422a, v40
	v_add_f32_e32 v49, v49, v49
	v_add_f32_e32 v40, v40, v40
	v_mul_f32_e32 v49, 0xbfb8aa3b, v49
	v_mul_f32_e32 v40, 0xbfb8aa3b, v40
	v_exp_f32_e32 v49, v49
	v_exp_f32_e32 v40, v40
	v_add_f32_e32 v49, 1.0, v49
	v_add_f32_e32 v40, 1.0, v40
	v_rcp_f32_e32 v55, v49
	v_rcp_f32_e32 v57, v40
	v_pk_mul_f32 v[46:47], v[46:47], v[54:55]
	v_pk_mul_f32 v[42:43], v[42:43], v[56:57]

.LBB0_952:
	v_cvt_pk_bf16_f32 v36, v36, v37
	v_cvt_pk_bf16_f32 v37, v38, v39
	v_cvt_pk_bf16_f32 v38, v32, v33
	v_cvt_pk_bf16_f32 v39, v34, v35
	global_store_dwordx4 v[40:41], v[36:39], off offset:256
	s_and_b64 vcc, exec, s[12:13]
	v_fmamk_f32 v32, v166, 0x3a800000, v227
	v_mul_f32_e32 v33, 0x4b800000, v32
	v_cmp_gt_f32_e64 s[16:17], s2, v32
	s_nop 1
	v_cndmask_b32_e64 v32, v32, v33, s[16:17]
	v_rsq_f32_e32 v32, v32
	s_nop 0
	v_mul_f32_e32 v33, 0x45800000, v32
	v_cndmask_b32_e64 v32, v32, v33, s[16:17]
	v_pk_mul_f32 v[30:31], v[30:31], v[32:33] op_sel_hi:[1,0]
	v_pk_mul_f32 v[34:35], v[28:29], v[32:33] op_sel_hi:[1,0]
	v_pk_mul_f32 v[26:27], v[26:27], v[32:33] op_sel_hi:[1,0]
	v_pk_mul_f32 v[28:29], v[24:25], v[32:33] op_sel_hi:[1,0]
	s_cbranch_vccnz .LBB0_954
	v_mul_f32_e32 v25, 0x3d372713, v28
	v_mul_f32_e32 v25, v28, v25
	v_fma_f32 v25, v28, v25, v28
	v_mul_f32_e32 v25, 0x3f4c422a, v25
	v_add_f32_e32 v25, v25, v25
	v_mul_f32_e32 v25, 0xbfb8aa3b, v25
	v_exp_f32_e32 v25, v25
	v_mov_b32_e32 v33, v35
	v_mov_b32_e32 v37, v29
	v_mul_f32_e32 v24, 0x3d372713, v34
	v_add_f32_e32 v25, 1.0, v25
	v_rcp_f32_e32 v36, v25
	v_mul_f32_e32 v25, 0x3d372713, v35
	v_mul_f32_e32 v25, v35, v25
	v_fmac_f32_e32 v33, v33, v25
	v_mul_f32_e32 v25, 0x3f4c422a, v33
	v_mul_f32_e32 v33, 0x3d372713, v29
	v_mul_f32_e32 v33, v29, v33
	v_fmac_f32_e32 v37, v37, v33
	v_mul_f32_e32 v33, 0x3f4c422a, v37
	v_add_f32_e32 v33, v33, v33
	v_mul_f32_e32 v33, 0xbfb8aa3b, v33
	v_exp_f32_e32 v33, v33
	v_mul_f32_e32 v24, v34, v24
	v_fma_f32 v24, v34, v24, v34
	v_mul_f32_e32 v24, 0x3f4c422a, v24
	v_add_f32_e32 v33, 1.0, v33
	v_rcp_f32_e32 v37, v33
	v_mul_f32_e32 v33, 0x3d372713, v30
	v_mul_f32_e32 v33, v30, v33
	v_fma_f32 v33, v30, v33, v30
	v_mul_f32_e32 v33, 0x3f4c422a, v33
	v_add_f32_e32 v33, v33, v33
	v_mul_f32_e32 v33, 0xbfb8aa3b, v33
	v_exp_f32_e32 v33, v33
	v_add_f32_e32 v24, v24, v24
	v_add_f32_e32 v25, v25, v25
	v_mul_f32_e32 v24, 0xbfb8aa3b, v24
	v_add_f32_e32 v33, 1.0, v33
	v_rcp_f32_e32 v38, v33
	v_mul_f32_e32 v33, 0x3d372713, v26
	v_mul_f32_e32 v25, 0xbfb8aa3b, v25
	v_mul_f32_e32 v33, v26, v33
	v_exp_f32_e32 v24, v24
	v_exp_f32_e32 v25, v25
	v_fma_f32 v33, v26, v33, v26
	v_mul_f32_e32 v33, 0x3f4c422a, v33
	v_add_f32_e32 v33, v33, v33
	v_mul_f32_e32 v33, 0xbfb8aa3b, v33
	v_add_f32_e32 v24, 1.0, v24
	v_add_f32_e32 v25, 1.0, v25
	v_exp_f32_e32 v33, v33
	v_rcp_f32_e32 v24, v24
	v_rcp_f32_e32 v25, v25
	v_pk_mul_f32 v[28:29], v[28:29], v[36:37]
	v_add_f32_e32 v33, 1.0, v33
	v_rcp_f32_e32 v40, v33
	v_mul_f32_e32 v33, 0x3d372713, v31
	v_pk_mul_f32 v[34:35], v[34:35], v[24:25]
	v_mul_f32_e32 v24, 0x3d372713, v27
	v_mul_f32_e32 v33, v31, v33
	v_mul_f32_e32 v24, v27, v24
	v_fma_f32 v33, v31, v33, v31
	v_fma_f32 v24, v27, v24, v27
	v_mul_f32_e32 v33, 0x3f4c422a, v33
	v_mul_f32_e32 v24, 0x3f4c422a, v24
	v_add_f32_e32 v33, v33, v33
	v_add_f32_e32 v24, v24, v24
	v_mul_f32_e32 v33, 0xbfb8aa3b, v33
	v_mul_f32_e32 v24, 0xbfb8aa3b, v24
	v_exp_f32_e32 v33, v33
	v_exp_f32_e32 v24, v24
	v_add_f32_e32 v33, 1.0, v33
	v_add_f32_e32 v24, 1.0, v24
	v_rcp_f32_e32 v39, v33
	v_rcp_f32_e32 v41, v24
	v_pk_mul_f32 v[30:31], v[30:31], v[38:39]
	v_pk_mul_f32 v[26:27], v[26:27], v[40:41]

.LBB0_956:
	v_cvt_pk_bf16_f32 v20, v20, v21
	v_cvt_pk_bf16_f32 v21, v22, v23
	v_cvt_pk_bf16_f32 v22, v16, v17
	v_cvt_pk_bf16_f32 v23, v18, v19
	global_store_dwordx4 v[24:25], v[20:23], off offset:256
	s_and_b64 vcc, exec, s[12:13]
	v_fmamk_f32 v16, v167, 0x3a800000, v227
	v_mul_f32_e32 v17, 0x4b800000, v16
	v_cmp_gt_f32_e64 s[16:17], s2, v16
	s_nop 1
	v_cndmask_b32_e64 v16, v16, v17, s[16:17]
	v_rsq_f32_e32 v16, v16
	s_nop 0
	v_mul_f32_e32 v17, 0x45800000, v16
	v_cndmask_b32_e64 v16, v16, v17, s[16:17]
	v_pk_mul_f32 v[14:15], v[14:15], v[16:17] op_sel_hi:[1,0]
	v_pk_mul_f32 v[18:19], v[12:13], v[16:17] op_sel_hi:[1,0]
	v_pk_mul_f32 v[10:11], v[10:11], v[16:17] op_sel_hi:[1,0]
	v_pk_mul_f32 v[12:13], v[8:9], v[16:17] op_sel_hi:[1,0]
	s_cbranch_vccnz .LBB0_958
	v_mul_f32_e32 v9, 0x3d372713, v12
	v_mul_f32_e32 v9, v12, v9
	v_fma_f32 v9, v12, v9, v12
	v_mul_f32_e32 v9, 0x3f4c422a, v9
	v_add_f32_e32 v9, v9, v9
	v_mul_f32_e32 v9, 0xbfb8aa3b, v9
	v_exp_f32_e32 v9, v9
	v_mov_b32_e32 v17, v19
	v_mov_b32_e32 v21, v13
	v_mul_f32_e32 v8, 0x3d372713, v18
	v_add_f32_e32 v9, 1.0, v9
	v_rcp_f32_e32 v20, v9
	v_mul_f32_e32 v9, 0x3d372713, v19
	v_mul_f32_e32 v9, v19, v9
	v_fmac_f32_e32 v17, v17, v9
	v_mul_f32_e32 v9, 0x3f4c422a, v17
	v_mul_f32_e32 v17, 0x3d372713, v13
	v_mul_f32_e32 v17, v13, v17
	v_fmac_f32_e32 v21, v21, v17
	v_mul_f32_e32 v17, 0x3f4c422a, v21
	v_add_f32_e32 v17, v17, v17
	v_mul_f32_e32 v17, 0xbfb8aa3b, v17
	v_exp_f32_e32 v17, v17
	v_mul_f32_e32 v8, v18, v8
	v_fma_f32 v8, v18, v8, v18
	v_mul_f32_e32 v8, 0x3f4c422a, v8
	v_add_f32_e32 v17, 1.0, v17
	v_rcp_f32_e32 v21, v17
	v_mul_f32_e32 v17, 0x3d372713, v14
	v_mul_f32_e32 v17, v14, v17
	v_fma_f32 v17, v14, v17, v14
	v_mul_f32_e32 v17, 0x3f4c422a, v17
	v_add_f32_e32 v17, v17, v17
	v_mul_f32_e32 v17, 0xbfb8aa3b, v17
	v_exp_f32_e32 v17, v17
	v_add_f32_e32 v8, v8, v8
	v_add_f32_e32 v9, v9, v9
	v_mul_f32_e32 v8, 0xbfb8aa3b, v8
	v_add_f32_e32 v17, 1.0, v17
	v_rcp_f32_e32 v22, v17
	v_mul_f32_e32 v17, 0x3d372713, v10
	v_mul_f32_e32 v9, 0xbfb8aa3b, v9
	v_mul_f32_e32 v17, v10, v17
	v_exp_f32_e32 v8, v8
	v_exp_f32_e32 v9, v9
	v_fma_f32 v17, v10, v17, v10
	v_mul_f32_e32 v17, 0x3f4c422a, v17
	v_add_f32_e32 v17, v17, v17
	v_mul_f32_e32 v17, 0xbfb8aa3b, v17
	v_add_f32_e32 v8, 1.0, v8
	v_add_f32_e32 v9, 1.0, v9
	v_exp_f32_e32 v17, v17
	v_rcp_f32_e32 v8, v8
	v_rcp_f32_e32 v9, v9
	v_pk_mul_f32 v[12:13], v[12:13], v[20:21]
	v_add_f32_e32 v17, 1.0, v17
	v_rcp_f32_e32 v24, v17
	v_mul_f32_e32 v17, 0x3d372713, v15
	v_pk_mul_f32 v[18:19], v[18:19], v[8:9]
	v_mul_f32_e32 v8, 0x3d372713, v11
	v_mul_f32_e32 v17, v15, v17
	v_mul_f32_e32 v8, v11, v8
	v_fma_f32 v17, v15, v17, v15
	v_fma_f32 v8, v11, v8, v11
	v_mul_f32_e32 v17, 0x3f4c422a, v17
	v_mul_f32_e32 v8, 0x3f4c422a, v8
	v_add_f32_e32 v17, v17, v17
	v_add_f32_e32 v8, v8, v8
	v_mul_f32_e32 v17, 0xbfb8aa3b, v17
	v_mul_f32_e32 v8, 0xbfb8aa3b, v8
	v_exp_f32_e32 v17, v17
	v_exp_f32_e32 v8, v8
	v_add_f32_e32 v17, 1.0, v17
	v_add_f32_e32 v8, 1.0, v8
	v_rcp_f32_e32 v23, v17
	v_rcp_f32_e32 v25, v8
	v_pk_mul_f32 v[14:15], v[14:15], v[22:23]
	v_pk_mul_f32 v[10:11], v[10:11], v[24:25]
